# select_row: chunk 2-7 score-to-key conversion as ashr+bitop3 in place, index masking only on the chunk straddling t
# speedup vs baseline: 1.0060x; 1.0034x over previous
; DI size_t sc_rowoff(int b, int t) { const int c = t >> 6; return (size_t)b * SC_PB + (size_t)4096 * (c * (c + 1) / 2) + (size_t)(t & 63) * (64 * (c + 1)); }
; DI void select_row(const float* SC, unsigned* dmask, int b, int t, int lane) {
;     ...
;     const int nch = (nvalid + 255) >> 8;
;     const float* srow = SC + sc_rowoff(b, t) + 4 * lane;
;     unsigned u[8][4];
; #pragma unroll
;     for (int k = 0; k < 8; ++k) {
;         if (k < nch) {
;             const f32x4 v = *(const f32x4*)(srow + 256 * k);
; #pragma unroll
;             for (int e = 0; e < 4; ++e) { const unsigned bits = __builtin_bit_cast(unsigned, v[e] + 0.0f); const unsigned key = ((int)bits < 0) ? ~bits : (bits | 0x80000000u);
;                 u[k][e] = (256 * k + 4 * lane + e <= t) ? key : 0u; }
;         } else { u[k][0] = 0u; u[k][1] = 0u; u[k][2] = 0u; u[k][3] = 0u; }
;     }
.Lsel_pf_done:
	s_mov_b32 s99, 0x80000000
	v_mov_b32_e32 v121, v43
	s_cmpk_gt_u32 s65, 0x1ff
	v_lshl_add_u64 v[10:11], s[8:9], 0, v[120:121]
	v_mov_b32_e32 v28, 0
	s_cselect_b64 s[10:11], -1, 0
	s_cmpk_lt_u32 s65, 0x200
	v_mov_b32_e32 v32, 0
	v_mov_b32_e32 v42, 0
	v_mov_b32_e32 v33, 0
	v_mov_b32_e32 v41, 0
	s_cbranch_scc1 .LBB0_539
	s_waitcnt vmcnt(0)
	v_pk_add_f32 v[150:151], v[150:151], 0 op_sel_hi:[1,0]
	v_pk_add_f32 v[152:153], v[152:153], 0 op_sel_hi:[1,0]
	v_ashrrev_i32_e32 v146, 31, v150
	v_ashrrev_i32_e32 v147, 31, v151
	v_ashrrev_i32_e32 v148, 31, v152
	v_ashrrev_i32_e32 v149, 31, v153
	v_bitop3_b32 v33, v150, v146, s99 bitop3:0x1e
	v_bitop3_b32 v41, v151, v147, s99 bitop3:0x1e
	v_bitop3_b32 v32, v152, v148, s99 bitop3:0x1e
	v_bitop3_b32 v42, v153, v149, s99 bitop3:0x1e
	s_cmpk_gt_u32 s65, 0x2fe
	s_cbranch_scc1 .Lsel_cv_2
	v_cmp_ge_u32_e32 vcc, s65, v86
	s_nop 1
	v_cndmask_b32_e32 v33, 0, v33, vcc
	v_cmp_ge_u32_e32 vcc, s65, v87
	s_nop 1
	v_cndmask_b32_e32 v41, 0, v41, vcc
	v_or_b32_e32 v12, 0x202, v88
	v_cmp_ge_u32_e32 vcc, s65, v12
	s_nop 1
	v_cndmask_b32_e32 v32, 0, v32, vcc
	v_cmp_ge_u32_e32 vcc, s65, v89
	s_nop 1
	v_cndmask_b32_e32 v42, 0, v42, vcc
.Lsel_cv_2:
.LBB0_539:
	s_cmpk_gt_u32 s65, 0x2ff
	s_cselect_b64 s[54:55], -1, 0
	s_cmpk_lt_u32 s65, 0x300
	v_mov_b32_e32 v31, 0
	v_mov_b32_e32 v29, 0
	v_mov_b32_e32 v30, 0
	s_cbranch_scc1 .LBB0_541
	s_waitcnt vmcnt(0)
	v_pk_add_f32 v[154:155], v[154:155], 0 op_sel_hi:[1,0]
	v_pk_add_f32 v[156:157], v[156:157], 0 op_sel_hi:[1,0]
	v_ashrrev_i32_e32 v146, 31, v154
	v_ashrrev_i32_e32 v147, 31, v155
	v_ashrrev_i32_e32 v148, 31, v156
	v_ashrrev_i32_e32 v149, 31, v157
	v_bitop3_b32 v29, v154, v146, s99 bitop3:0x1e
	v_bitop3_b32 v30, v155, v147, s99 bitop3:0x1e
	v_bitop3_b32 v28, v156, v148, s99 bitop3:0x1e
	v_bitop3_b32 v31, v157, v149, s99 bitop3:0x1e
	s_cmpk_gt_u32 s65, 0x3fe
	s_cbranch_scc1 .Lsel_cv_3
	v_cmp_ge_u32_e32 vcc, s65, v98
	s_nop 1
	v_cndmask_b32_e32 v29, 0, v29, vcc
	v_cmp_ge_u32_e32 vcc, s65, v91
	s_nop 1
	v_cndmask_b32_e32 v30, 0, v30, vcc
	v_cmp_ge_u32_e32 vcc, s65, v100
	s_nop 1
	v_cndmask_b32_e32 v28, 0, v28, vcc
	v_cmp_ge_u32_e32 vcc, s65, v93
	s_nop 1
	v_cndmask_b32_e32 v31, 0, v31, vcc
.Lsel_cv_3:
.LBB0_541:
	s_cmpk_gt_u32 s65, 0x3ff
	v_mov_b32_e32 v18, 0
	s_cselect_b64 s[76:77], -1, 0
	s_cmpk_lt_u32 s65, 0x400
	v_mov_b32_e32 v26, 0
	v_mov_b32_e32 v27, 0
	v_mov_b32_e32 v24, 0
	v_mov_b32_e32 v25, 0
	s_cbranch_scc1 .LBB0_543
	v_add_co_u32_e32 v12, vcc, 0x1000, v10
	s_nop 1
	v_addc_co_u32_e32 v13, vcc, 0, v11, vcc
	s_waitcnt vmcnt(0)
	v_pk_add_f32 v[158:159], v[158:159], 0 op_sel_hi:[1,0]
	v_pk_add_f32 v[160:161], v[160:161], 0 op_sel_hi:[1,0]
	v_ashrrev_i32_e32 v146, 31, v158
	v_ashrrev_i32_e32 v147, 31, v159
	v_ashrrev_i32_e32 v148, 31, v160
	v_ashrrev_i32_e32 v149, 31, v161
	v_bitop3_b32 v24, v158, v146, s99 bitop3:0x1e
	v_bitop3_b32 v25, v159, v147, s99 bitop3:0x1e
	v_bitop3_b32 v26, v160, v148, s99 bitop3:0x1e
	v_bitop3_b32 v27, v161, v149, s99 bitop3:0x1e
	s_cmpk_gt_u32 s65, 0x4fe
	s_cbranch_scc1 .Lsel_cv_4
	v_cmp_ge_u32_e32 vcc, s65, v102
	s_nop 1
	v_cndmask_b32_e32 v24, 0, v24, vcc
	v_or_b32_e32 v13, 0x401, v88
	v_cmp_ge_u32_e32 vcc, s65, v13
	s_nop 1
	v_cndmask_b32_e32 v25, 0, v25, vcc
	v_cmp_ge_u32_e32 vcc, s65, v104
	s_nop 1
	v_cndmask_b32_e32 v26, 0, v26, vcc
	v_or_b32_e32 v13, 0x403, v88
	v_cmp_ge_u32_e32 vcc, s65, v13
	s_nop 1
	v_cndmask_b32_e32 v27, 0, v27, vcc
.Lsel_cv_4:
.LBB0_543:
	s_cmpk_gt_u32 s65, 0x4ff
	s_cselect_b64 s[52:53], -1, 0
	s_cmpk_lt_u32 s65, 0x500
	v_mov_b32_e32 v23, 0
	v_mov_b32_e32 v21, 0
	v_mov_b32_e32 v22, 0
	s_cbranch_scc1 .LBB0_545
	v_add_co_u32_e32 v12, vcc, 0x1000, v10
	s_nop 1
	v_addc_co_u32_e32 v13, vcc, 0, v11, vcc
	s_waitcnt vmcnt(0)
	v_pk_add_f32 v[162:163], v[162:163], 0 op_sel_hi:[1,0]
	v_pk_add_f32 v[164:165], v[164:165], 0 op_sel_hi:[1,0]
	v_ashrrev_i32_e32 v146, 31, v162
	v_ashrrev_i32_e32 v147, 31, v163
	v_ashrrev_i32_e32 v148, 31, v164
	v_ashrrev_i32_e32 v149, 31, v165
	v_bitop3_b32 v21, v162, v146, s99 bitop3:0x1e
	v_bitop3_b32 v22, v163, v147, s99 bitop3:0x1e
	v_bitop3_b32 v18, v164, v148, s99 bitop3:0x1e
	v_bitop3_b32 v23, v165, v149, s99 bitop3:0x1e
	s_cmpk_gt_u32 s65, 0x5fe
	s_cbranch_scc1 .Lsel_cv_5
	v_cmp_ge_u32_e32 vcc, s65, v106
	s_nop 1
	v_cndmask_b32_e32 v21, 0, v21, vcc
	v_cmp_ge_u32_e32 vcc, s65, v99
	s_nop 1
	v_cndmask_b32_e32 v22, 0, v22, vcc
	v_cmp_ge_u32_e32 vcc, s65, v108
	s_nop 1
	v_cndmask_b32_e32 v18, 0, v18, vcc
	v_cmp_ge_u32_e32 vcc, s65, v101
	s_nop 1
	v_cndmask_b32_e32 v23, 0, v23, vcc
; DI void select_row(const float* SC, unsigned* dmask, int b, int t, int lane) {
;     ...
;     for (int k = 0; k < 8; ++k) {
;         if (k < nch) {
;             const f32x4 v = *(const f32x4*)(srow + 256 * k);
; #pragma unroll
;             for (int e = 0; e < 4; ++e) { const unsigned bits = __builtin_bit_cast(unsigned, v[e] + 0.0f); const unsigned key = ((int)bits < 0) ? ~bits : (bits | 0x80000000u);
;                 u[k][e] = (256 * k + 4 * lane + e <= t) ? key : 0u; }
;         } else { u[k][0] = 0u; u[k][1] = 0u; u[k][2] = 0u; u[k][3] = 0u; }
;     }
.Lsel_cv_5:
.LBB0_545:
	s_cmpk_gt_u32 s65, 0x5ff
	v_mov_b32_e32 v12, 0
	s_cselect_b64 s[80:81], -1, 0
	s_cmpk_lt_u32 s65, 0x600
	v_mov_b32_e32 v19, 0
	v_mov_b32_e32 v20, 0
	v_mov_b32_e32 v15, 0
	v_mov_b32_e32 v16, 0
	s_cbranch_scc1 .LBB0_547
	v_add_co_u32_e32 v14, vcc, 0x1000, v10
	s_nop 1
	v_addc_co_u32_e32 v15, vcc, 0, v11, vcc
	s_waitcnt vmcnt(0)
	v_pk_add_f32 v[166:167], v[166:167], 0 op_sel_hi:[1,0]
	v_pk_add_f32 v[168:169], v[168:169], 0 op_sel_hi:[1,0]
	v_ashrrev_i32_e32 v146, 31, v166
	v_ashrrev_i32_e32 v147, 31, v167
	v_ashrrev_i32_e32 v148, 31, v168
	v_ashrrev_i32_e32 v149, 31, v169
	v_bitop3_b32 v15, v166, v146, s99 bitop3:0x1e
	v_bitop3_b32 v16, v167, v147, s99 bitop3:0x1e
	v_bitop3_b32 v19, v168, v148, s99 bitop3:0x1e
	v_bitop3_b32 v20, v169, v149, s99 bitop3:0x1e
	s_cmpk_gt_u32 s65, 0x6fe
	s_cbranch_scc1 .Lsel_cv_6
	v_cmp_ge_u32_e32 vcc, s65, v110
	s_nop 1
	v_cndmask_b32_e32 v15, 0, v15, vcc
	v_cmp_ge_u32_e32 vcc, s65, v103
	s_nop 1
	v_cndmask_b32_e32 v16, 0, v16, vcc
	v_cmp_ge_u32_e32 vcc, s65, v112
	s_nop 1
	v_cndmask_b32_e32 v19, 0, v19, vcc
	v_cmp_ge_u32_e32 vcc, s65, v105
	s_nop 1
	v_cndmask_b32_e32 v20, 0, v20, vcc
.Lsel_cv_6:
.LBB0_547:
	s_cmpk_gt_u32 s65, 0x6ff
	s_cselect_b64 s[50:51], -1, 0
	s_cmpk_lt_u32 s65, 0x700
	v_mov_b32_e32 v17, 0
	v_mov_b32_e32 v13, 0
	v_mov_b32_e32 v14, 0
	s_cbranch_scc1 .LBB0_549
	s_waitcnt vmcnt(0)
	v_pk_add_f32 v[170:171], v[170:171], 0 op_sel_hi:[1,0]
	v_pk_add_f32 v[172:173], v[172:173], 0 op_sel_hi:[1,0]
	v_ashrrev_i32_e32 v146, 31, v170
	v_ashrrev_i32_e32 v147, 31, v171
	v_ashrrev_i32_e32 v148, 31, v172
	v_ashrrev_i32_e32 v149, 31, v173
	v_bitop3_b32 v13, v170, v146, s99 bitop3:0x1e
	v_bitop3_b32 v14, v171, v147, s99 bitop3:0x1e
	v_bitop3_b32 v12, v172, v148, s99 bitop3:0x1e
	v_bitop3_b32 v17, v173, v149, s99 bitop3:0x1e
	s_cmpk_gt_u32 s65, 0x7fe
	s_cbranch_scc1 .Lsel_cv_7
	v_cmp_ge_u32_e32 vcc, s65, v114
	s_nop 1
	v_cndmask_b32_e32 v13, 0, v13, vcc
	v_cmp_ge_u32_e32 vcc, s65, v107
	s_nop 1
	v_cndmask_b32_e32 v14, 0, v14, vcc
	v_cmp_ge_u32_e32 vcc, s65, v116
	s_nop 1
	v_cndmask_b32_e32 v12, 0, v12, vcc
	v_cmp_ge_u32_e32 vcc, s65, v109
	s_nop 1
	v_cndmask_b32_e32 v17, 0, v17, vcc
.Lsel_cv_7:
.LBB0_549:
	s_waitcnt vmcnt(1)
	v_pk_add_f32 v[6:7], v[6:7], 0 op_sel_hi:[1,0]
	s_waitcnt vmcnt(0)
	v_pk_add_f32 v[2:3], v[2:3], 0 op_sel_hi:[1,0]
	v_and_b32_e32 v11, 0x7fffffff, v7
	v_and_b32_e32 v10, 0x7fffffff, v6
	v_xor_b32_e32 v1, -1, v7
	v_pk_add_f32 v[34:35], v[10:11], 0 neg_lo:[1,1] neg_hi:[1,1]
	v_cmp_gt_i32_e32 vcc, 0, v7
	v_xor_b32_e32 v75, -1, v6
	s_nop 0
	v_cndmask_b32_e32 v10, v35, v1, vcc
	v_cmp_gt_i32_e32 vcc, 0, v6
	v_pk_add_f32 v[6:7], v[8:9], 0 op_sel_hi:[1,0]
	s_nop 0
	v_and_b32_e32 v9, 0x7fffffff, v7
	v_and_b32_e32 v8, 0x7fffffff, v6
	v_cndmask_b32_e32 v11, v34, v75, vcc
	v_xor_b32_e32 v1, -1, v7
	v_pk_add_f32 v[8:9], v[8:9], 0 neg_lo:[1,1] neg_hi:[1,1]
	v_cmp_gt_i32_e32 vcc, 0, v7
	v_xor_b32_e32 v34, -1, v6
	v_and_b32_e32 v7, 0x7fffffff, v3
	v_cndmask_b32_e32 v9, v9, v1, vcc
	v_cmp_gt_i32_e32 vcc, 0, v6
	v_and_b32_e32 v6, 0x7fffffff, v2
	v_pk_add_f32 v[6:7], v[6:7], 0 neg_lo:[1,1] neg_hi:[1,1]
	v_cndmask_b32_e32 v121, v8, v34, vcc
	v_xor_b32_e32 v8, -1, v2
	v_cmp_gt_i32_e32 vcc, 0, v2
	v_xor_b32_e32 v1, -1, v3
	s_nop 0
	v_cndmask_b32_e32 v2, v6, v8, vcc
	v_cmp_gt_i32_e32 vcc, 0, v3
	s_nop 1
	v_cndmask_b32_e32 v1, v7, v1, vcc
	v_cmp_ge_u32_e32 vcc, s65, v83
	s_nop 1
	v_cndmask_b32_e32 v6, 0, v1, vcc
	v_cmp_ge_u32_e32 vcc, s65, v90
	s_nop 1
	v_cndmask_b32_e32 v7, 0, v2, vcc
	v_pk_add_f32 v[2:3], v[4:5], 0 op_sel_hi:[1,0]
	s_nop 0
	v_and_b32_e32 v5, 0x7fffffff, v3
	v_and_b32_e32 v4, 0x7fffffff, v2
	v_xor_b32_e32 v8, -1, v2
	v_pk_add_f32 v[4:5], v[4:5], 0 neg_lo:[1,1] neg_hi:[1,1]
	v_cmp_gt_i32_e32 vcc, 0, v2
	v_xor_b32_e32 v1, -1, v3
	s_nop 0
	v_cndmask_b32_e32 v2, v4, v8, vcc
	v_cmp_gt_i32_e32 vcc, 0, v3
	s_nop 1
	v_cndmask_b32_e32 v1, v5, v1, vcc
	v_cmp_ge_u32_e32 vcc, s65, v85
	s_nop 1
	v_cndmask_b32_e32 v5, 0, v1, vcc
	v_cmp_ge_u32_e32 vcc, s65, v92
	v_mov_b32_e32 v1, v43
	s_nop 0
	v_cndmask_b32_e32 v8, 0, v2, vcc
	v_cmp_le_u32_e32 vcc, s62, v11
	v_addc_co_u32_e32 v1, vcc, 0, v1, vcc
	v_cndmask_b32_e64 v2, 0, 1, s[10:11]
	v_cmp_le_u32_e32 vcc, s62, v10
	v_addc_co_u32_e32 v1, vcc, 0, v1, vcc
	v_cmp_ne_u32_e64 s[82:83], 1, v2
	v_cmp_le_u32_e32 vcc, s62, v121
	v_addc_co_u32_e32 v1, vcc, 0, v1, vcc
	v_cmp_le_u32_e32 vcc, s62, v9
	v_addc_co_u32_e32 v1, vcc, 0, v1, vcc
	v_cmp_le_u32_e32 vcc, s62, v7
	v_addc_co_u32_e32 v1, vcc, 0, v1, vcc
	v_cmp_le_u32_e32 vcc, s62, v6
	v_addc_co_u32_e32 v1, vcc, 0, v1, vcc
	v_cmp_le_u32_e32 vcc, s62, v8
	v_addc_co_u32_e32 v1, vcc, 0, v1, vcc
	v_cmp_le_u32_e32 vcc, s62, v5
	v_addc_co_u32_e32 v1, vcc, 0, v1, vcc
	s_andn2_b64 vcc, exec, s[10:11]
	s_cbranch_vccnz .LBB0_566
	v_cmp_le_u32_e32 vcc, s62, v33
	v_addc_co_u32_e32 v1, vcc, 0, v1, vcc
	v_cmp_le_u32_e32 vcc, s62, v41
	v_addc_co_u32_e32 v1, vcc, 0, v1, vcc
	v_cmp_le_u32_e32 vcc, s62, v32
	v_addc_co_u32_e32 v1, vcc, 0, v1, vcc
	v_cmp_le_u32_e32 vcc, s62, v42
	v_addc_co_u32_e32 v1, vcc, 0, v1, vcc
	v_cmp_le_u32_e32 vcc, s62, v29
	v_addc_co_u32_e32 v1, vcc, 0, v1, vcc
	v_cmp_le_u32_e32 vcc, s62, v30
	v_addc_co_u32_e32 v1, vcc, 0, v1, vcc
	v_cmp_le_u32_e32 vcc, s62, v28
	v_addc_co_u32_e32 v1, vcc, 0, v1, vcc
	v_cmp_le_u32_e32 vcc, s62, v31
	v_addc_co_u32_e32 v1, vcc, 0, v1, vcc
	v_cndmask_b32_e64 v2, 0, 1, s[76:77]
	v_cmp_ne_u32_e64 s[78:79], 1, v2
	s_andn2_b64 vcc, exec, s[76:77]
	s_cbranch_vccz .LBB0_567
